# grid barrier: the 20 transitions with XCD-local data flow skip the cross-XCD level and L2 write-back (enabled only after a run-time placement check)
# speedup vs baseline: 1.0223x; 1.0183x over previous
.LBB0_2:
	s_or_b64 exec, exec, s[6:7]
	s_waitcnt lgkmcnt(0)
	s_barrier
	s_add_u32 s4, s62, 0x15e01000
	s_getreg_b32 s3, hwreg(HW_REG_XCC_ID, 0, 4)
	s_addc_u32 s5, s63, 0
	s_and_b32 s8, s3, 15
	s_mov_b64 s[12:13], exec
	v_readlane_b32 s6, v252, 0
	v_readlane_b32 s7, v252, 1
	s_and_b64 s[6:7], s[12:13], s[6:7]
	s_mov_b64 exec, s[6:7]
	s_cbranch_execz .LBB0_5
	s_mov_b64 s[6:7], exec
	v_mbcnt_lo_u32_b32 v1, s6, 0
	v_mbcnt_hi_u32_b32 v1, s7, v1
	v_cmp_eq_u32_e32 vcc, 0, v1
	s_and_b64 s[10:11], exec, vcc
	s_mov_b64 exec, s[10:11]
	s_cbranch_execz .LBB0_5
	s_lshl_b32 s9, s8, 8
	s_bcnt1_i32_b64 s6, s[6:7]
	v_mov_b32_e32 v1, s9
	v_mov_b32_e32 v2, s6
	global_atomic_add v1, v2, s[4:5] offset:1024
	s_and_b32 s9, s2, 7
	s_lshl_b32 s9, s9, 2
	s_addk_i32 s9, 0x3600
	s_lshl_b32 s6, 1, s8
	v_mov_b32_e32 v1, s9
	v_mov_b32_e32 v2, s6
	global_atomic_or v1, v2, s[4:5]
.LBB0_5:
	s_or_b64 exec, exec, s[12:13]
	s_load_dwordx2 s[6:7], s[0:1], 0xd0
	s_waitcnt lgkmcnt(0)
	s_cmp_ge_i32 s6, s7
	s_cbranch_scc1 .LBB0_549
	s_add_u32 s10, s0, 0xd8
	s_addc_u32 s11, s1, 0
	v_writelane_b32 v252, s10, 2
	s_load_dwordx16 s[36:51], s[0:1], 0x0
	v_mbcnt_lo_u32_b32 v2, -1, 0
	v_writelane_b32 v252, s11, 3
	s_add_u32 s10, s62, 0x15e01200
	s_addc_u32 s11, s63, 0
	v_writelane_b32 v252, s10, 4
	s_mov_b32 s17, s6
	v_mov_b32_e32 v131, 0
	v_writelane_b32 v252, s11, 5
	s_add_u32 s10, s62, 0x15e01400
	s_addc_u32 s11, s63, 0
	v_writelane_b32 v252, s10, 6
	v_mov_b32_e32 v1, 1
	v_mov_b32_e32 v197, 0x358637bd
	v_writelane_b32 v252, s11, 7
	s_add_u32 s10, s62, 0x15e01500
	s_addc_u32 s11, s63, 0
	v_writelane_b32 v252, s10, 8
	v_mbcnt_hi_u32_b32 v198, -1, v2
	v_mov_b32_e32 v199, 0x3ff
	v_writelane_b32 v252, s11, 9
	s_add_u32 s10, s62, 0x15e01600
	s_addc_u32 s11, s63, 0
	v_writelane_b32 v252, s10, 10
	v_mov_b32_e32 v200, 0xc000
	v_mov_b32_e32 v203, 0x41b17218
	v_writelane_b32 v252, s11, 11
	s_add_u32 s10, s62, 0x15e01700
	s_addc_u32 s11, s63, 0
	v_writelane_b32 v252, s10, 12
	v_mov_b32_e32 v204, 0x6000
	s_movk_i32 s33, 0x1000
	v_writelane_b32 v252, s11, 13
	s_add_u32 s10, s62, 0x15e01800
	s_addc_u32 s11, s63, 0
	v_writelane_b32 v252, s10, 14
	s_movk_i32 s26, 0x7fff
	s_movk_i32 s85, 0x104
	v_writelane_b32 v252, s11, 15
	s_add_u32 s10, s62, 0x15e01900
	s_addc_u32 s11, s63, 0
	v_writelane_b32 v252, s10, 16
	s_movk_i32 s12, 0xc00
	s_movk_i32 s15, 0x28c0
	v_writelane_b32 v252, s11, 17
	s_add_u32 s10, s62, 0x15e01a00
	s_addc_u32 s11, s63, 0
	v_writelane_b32 v252, s10, 18
	s_mov_b32 s14, 0x800000
	s_mov_b32 s18, 0x3e38aa3b
	v_writelane_b32 v252, s11, 19
	s_add_u32 s10, s62, 0x15e01b00
	s_addc_u32 s11, s63, 0
	v_writelane_b32 v252, s10, 20
	s_mov_b32 s19, 0xffff0000
	s_movk_i32 s23, 0x110
	v_writelane_b32 v252, s11, 21
	s_add_u32 s10, s62, 0x15e01c00
	s_addc_u32 s11, s63, 0
	v_writelane_b32 v252, s10, 22
	s_mov_b32 s93, 0
	s_mov_b64 s[98:99], 0x80
	v_writelane_b32 v252, s11, 23
	s_add_u32 s10, s62, 0x15e01d00
	s_addc_u32 s11, s63, 0
	v_writelane_b32 v252, s10, 24
	s_mov_b64 s[70:71], 0x100
	s_mov_b64 s[72:73], 0x180
	v_writelane_b32 v252, s11, 25
	s_add_u32 s10, s62, 0x15e01e00
	s_addc_u32 s11, s63, 0
	v_writelane_b32 v252, s10, 26
	s_mov_b64 s[74:75], 0x200
	s_mov_b64 s[76:77], 0x280
	v_writelane_b32 v252, s11, 27
	s_add_u32 s10, s62, 0x15e01f00
	s_addc_u32 s11, s63, 0
	v_writelane_b32 v252, s10, 28
	s_mov_b64 s[78:79], 0x300
	s_mov_b64 s[80:81], 0x380
	v_writelane_b32 v252, s11, 29
	s_add_u32 s10, s62, 0x15e02000
	s_addc_u32 s11, s63, 0
	v_writelane_b32 v252, s10, 30
	s_mov_b64 s[90:91], 0x400
	s_mov_b64 s[82:83], 0x780
	v_writelane_b32 v252, s11, 31
	s_add_u32 s10, s62, 0x15e02100
	s_addc_u32 s11, s63, 0
	v_writelane_b32 v252, s10, 32
	s_nop 1
	v_writelane_b32 v252, s11, 33
	s_add_u32 s10, s62, 0x15e02200
	s_addc_u32 s11, s63, 0
	v_writelane_b32 v252, s10, 34
	s_nop 1
	v_writelane_b32 v252, s11, 35
	s_add_u32 s10, s62, 0x15e02300
	s_addc_u32 s11, s63, 0
	v_writelane_b32 v252, s10, 36
	s_cmp_eq_u32 s8, 15
	s_nop 0
	v_writelane_b32 v252, s11, 37
	s_cselect_b64 s[10:11], -1, 0
	v_writelane_b32 v252, s10, 38
	s_cmp_eq_u32 s8, 14
	s_nop 0
	v_writelane_b32 v252, s11, 39
	s_cselect_b64 s[10:11], -1, 0
	v_writelane_b32 v252, s10, 40
	s_cmp_eq_u32 s8, 13
	s_nop 0
	v_writelane_b32 v252, s11, 41
	s_cselect_b64 s[10:11], -1, 0
	v_writelane_b32 v252, s10, 42
	s_cmp_eq_u32 s8, 12
	s_nop 0
	v_writelane_b32 v252, s11, 43
	s_cselect_b64 s[10:11], -1, 0
	v_writelane_b32 v252, s10, 44
	s_cmp_eq_u32 s8, 11
	s_nop 0
	v_writelane_b32 v252, s11, 45
	s_cselect_b64 s[10:11], -1, 0
	v_writelane_b32 v252, s10, 46
	s_cmp_eq_u32 s8, 10
	s_nop 0
	v_writelane_b32 v252, s11, 47
	s_cselect_b64 s[10:11], -1, 0
	v_writelane_b32 v252, s10, 48
	s_cmp_eq_u32 s8, 9
	s_nop 0
	v_writelane_b32 v252, s11, 49
	s_cselect_b64 s[10:11], -1, 0
	v_writelane_b32 v252, s10, 50
	s_cmp_eq_u32 s8, 8
	s_nop 0
	v_writelane_b32 v252, s11, 51
	s_cselect_b64 s[10:11], -1, 0
	v_writelane_b32 v252, s10, 52
	s_cmp_eq_u32 s8, 7
	s_nop 0
	v_writelane_b32 v252, s11, 53
	s_cselect_b64 s[10:11], -1, 0
	v_writelane_b32 v252, s10, 54
	s_cmp_eq_u32 s8, 6
	s_nop 0
	v_writelane_b32 v252, s11, 55
	s_cselect_b64 s[10:11], -1, 0
	v_writelane_b32 v252, s10, 56
	s_cmp_eq_u32 s8, 5
	s_nop 0
	v_writelane_b32 v252, s11, 57
	s_cselect_b64 s[10:11], -1, 0
	v_writelane_b32 v252, s10, 58
	s_cmp_eq_u32 s8, 4
	s_nop 0
	v_writelane_b32 v252, s11, 59
	s_cselect_b64 s[10:11], -1, 0
	v_writelane_b32 v252, s10, 60
	s_cmp_eq_u32 s8, 3
	s_nop 0
	v_writelane_b32 v252, s11, 61
	s_cselect_b64 s[10:11], -1, 0
	v_writelane_b32 v252, s10, 62
	s_cmp_eq_u32 s8, 2
	s_nop 0
	v_writelane_b32 v252, s11, 63
	s_cselect_b64 s[10:11], -1, 0
	v_writelane_b32 v253, s10, 0
	s_cmp_eq_u32 s8, 1
	s_nop 0
	v_writelane_b32 v253, s11, 1
	s_cselect_b64 s[10:11], -1, 0
	v_writelane_b32 v253, s10, 2
	s_cmp_eq_u32 s8, 0
	s_nop 0
	v_writelane_b32 v253, s11, 3
	s_cselect_b64 s[10:11], -1, 0
	s_lshl_b32 s3, s8, 8
	s_add_u32 s4, s4, s3
	s_addc_u32 s3, s5, 0
	v_writelane_b32 v253, s10, 4
	s_add_u32 s8, s4, 0x1400
	s_addc_u32 s9, s3, 0
	v_writelane_b32 v253, s11, 5
	v_writelane_b32 v253, s8, 6
	s_add_u32 s4, s4, 0x2400
	s_addc_u32 s5, s3, 0
	v_writelane_b32 v253, s9, 7
	v_writelane_b32 v253, s4, 8
	s_nop 1
	v_writelane_b32 v253, s5, 9
	s_add_u32 s4, s62, 0x15e04400
	s_addc_u32 s5, s63, 0
	v_writelane_b32 v253, s4, 10
	s_nop 1
	v_writelane_b32 v253, s5, 11
	s_add_u32 s4, s62, 0x15e04500
	s_addc_u32 s5, s63, 0
	v_writelane_b32 v253, s4, 12
	s_nop 1
	v_writelane_b32 v253, s5, 13
	s_add_u32 s4, s62, 0x80000
	s_addc_u32 s5, s63, 0
	v_writelane_b32 v253, s4, 14
	s_nop 1
	v_writelane_b32 v253, s5, 15
	s_add_u32 s4, s62, 0xf680000
	s_addc_u32 s5, s63, 0
	v_writelane_b32 v253, s4, 16
	s_nop 1
	v_writelane_b32 v253, s5, 17
	s_add_u32 s4, s62, 0xe680000
	s_addc_u32 s5, s63, 0
	s_add_u32 s8, s62, 0x2080000
	v_writelane_b32 v253, s4, 18
	s_addc_u32 s9, s63, 0
	s_nop 0
	v_writelane_b32 v253, s5, 19
	s_add_u32 s4, s62, 0x7e00000
	s_addc_u32 s5, s63, 0
	v_writelane_b32 v253, s4, 20
	s_nop 1
	v_writelane_b32 v253, s5, 21
	s_add_u32 s4, s62, 0x9e40000
	s_addc_u32 s5, s63, 0
	v_writelane_b32 v253, s4, 22
	s_nop 1
	v_writelane_b32 v253, s5, 23
	s_add_u32 s4, s62, 0xce80000
	s_addc_u32 s5, s63, 0
	v_writelane_b32 v253, s4, 24
	s_nop 1
	v_writelane_b32 v253, s5, 25
	s_add_u32 s4, s62, 0x1080000
	s_addc_u32 s5, s63, 0
	v_writelane_b32 v253, s4, 26
	s_nop 1
	v_writelane_b32 v253, s5, 27
	s_add_u32 s4, s62, 0xde80000
	s_addc_u32 s5, s63, 0
	s_add_u32 s68, s62, 0x9e80000
	v_writelane_b32 v253, s4, 28
	s_addc_u32 s69, s63, 0
	s_nop 0
	v_writelane_b32 v253, s5, 29
	s_add_u32 s4, s62, 0x9600000
	s_addc_u32 s5, s63, 0
	v_writelane_b32 v253, s4, 30
	s_nop 1
	v_writelane_b32 v253, s5, 31
	s_add_u32 s4, s62, 0x7200000
	s_addc_u32 s5, s63, 0
	v_writelane_b32 v253, s4, 32
	s_nop 1
	v_writelane_b32 v253, s5, 33
	s_add_u32 s4, s62, 0x7c00000
	s_addc_u32 s5, s63, 0
	v_writelane_b32 v253, s4, 34
	s_nop 1
	v_writelane_b32 v253, s5, 35
	s_add_u32 s4, s62, 0x15d81000
	s_addc_u32 s5, s63, 0
	v_writelane_b32 v253, s4, 36
	s_nop 1
	v_writelane_b32 v253, s5, 37
	s_add_u32 s4, s62, 0x15d01000
	s_addc_u32 s5, s63, 0
	v_writelane_b32 v253, s4, 38
	s_nop 1
	v_writelane_b32 v253, s5, 39
	s_add_u32 s4, s62, 0x7a00000
	s_addc_u32 s5, s63, 0
	v_writelane_b32 v253, s4, 40
	s_nop 1
	v_writelane_b32 v253, s5, 41
	s_add_u32 s4, s62, 0x154e0000
	s_addc_u32 s5, s63, 0
	v_writelane_b32 v253, s4, 42
	s_nop 1
	v_writelane_b32 v253, s5, 43
	s_add_u32 s4, s62, 0x15ce0000
	s_addc_u32 s5, s63, 0
	v_writelane_b32 v253, s4, 44
	s_add_u32 s3, s60, 0x3000000
	s_nop 0
	v_writelane_b32 v253, s5, 45
	v_writelane_b32 v253, s3, 46
	s_addc_u32 s3, s61, 0
	s_add_u32 s86, s62, 0x15d00000
	s_addc_u32 s87, s63, 0
	v_writelane_b32 v253, s3, 47
	s_add_u32 s3, s60, 0x3400000
	v_writelane_b32 v253, s3, 48
	s_addc_u32 s3, s61, 0
	s_add_u32 s4, s62, 0x9e00000
	v_writelane_b32 v253, s3, 49
	s_addc_u32 s5, s63, 0
	v_writelane_b32 v253, s4, 50
	s_nop 1
	v_writelane_b32 v253, s5, 51
	s_add_u32 s4, s60, 0x2000000
	s_addc_u32 s5, s61, 0
	v_writelane_b32 v253, s4, 52
	s_nop 1
	v_writelane_b32 v253, s5, 53
	s_add_u32 s4, s60, 0x2800000
	s_addc_u32 s5, s61, 0
	v_writelane_b32 v253, s4, 54
	s_nop 1
	v_writelane_b32 v253, s5, 55
	s_add_u32 s4, s62, 0x10898000
	s_addc_u32 s5, s63, 0
	v_writelane_b32 v253, s4, 56
	s_nop 1
	v_writelane_b32 v253, s5, 57
	s_add_u32 s4, s62, 0x10318000
	s_addc_u32 s5, s63, 0
	v_writelane_b32 v253, s4, 58
	s_nop 1
	v_writelane_b32 v253, s5, 59
	s_add_u32 s4, s62, 0xfd98000
	s_addc_u32 s5, s63, 0
	v_writelane_b32 v253, s4, 60
	s_nop 1
	v_writelane_b32 v253, s5, 61
	s_add_u32 s4, s62, 0xfb98000
	s_addc_u32 s5, s63, 0
	s_add_u32 s3, s62, 0x80
	v_writelane_b32 v254, s3, 0
	s_addc_u32 s3, s63, 0
	v_writelane_b32 v254, s3, 1
	s_add_u32 s3, s62, 0xf680080
	v_writelane_b32 v254, s3, 2
	s_addc_u32 s3, s63, 0
	v_writelane_b32 v254, s3, 3
	s_add_i32 s3, 0, 0x12ff0
	v_writelane_b32 v253, s4, 62
	v_writelane_b32 v254, s3, 4
	s_add_i32 s3, 0, 0x12ff4
	v_writelane_b32 v253, s5, 63
	v_writelane_b32 v254, s3, 5
	s_add_i32 s4, 0, 0x8200
	v_writelane_b32 v254, s4, 6
	s_add_i32 s4, 0, 0x10500
	v_writelane_b32 v254, s4, 7
	s_add_i32 s4, 0, 0x10700
	v_writelane_b32 v254, s4, 8
	s_add_i32 s4, 0, 0x10600
	v_writelane_b32 v254, s4, 9
	s_add_i32 s4, 0, 0x105fc
	v_writelane_b32 v254, s4, 10
	s_waitcnt lgkmcnt(0)
	v_writelane_b32 v254, s36, 11
	s_movk_i32 s3, 0x6000
	s_add_i32 s84, 0, 0x10400
	v_writelane_b32 v254, s37, 12
	v_writelane_b32 v254, s38, 13
	v_writelane_b32 v254, s39, 14
	v_writelane_b32 v254, s40, 15
	v_writelane_b32 v254, s41, 16
	v_writelane_b32 v254, s42, 17
	v_writelane_b32 v254, s43, 18
	v_writelane_b32 v254, s44, 19
	v_writelane_b32 v254, s45, 20
	v_writelane_b32 v254, s46, 21
	v_writelane_b32 v254, s47, 22
	v_writelane_b32 v254, s48, 23
	v_writelane_b32 v254, s49, 24
	v_writelane_b32 v254, s50, 25
	v_writelane_b32 v254, s51, 26
	s_load_dwordx16 s[36:51], s[0:1], 0x40
	s_waitcnt lgkmcnt(0)
	v_writelane_b32 v254, s36, 27
	s_nop 1
	v_writelane_b32 v254, s37, 28
	v_writelane_b32 v254, s38, 29
	v_writelane_b32 v254, s39, 30
	v_writelane_b32 v254, s40, 31
	v_writelane_b32 v254, s41, 32
	v_writelane_b32 v254, s42, 33
	v_writelane_b32 v254, s43, 34
	v_writelane_b32 v254, s44, 35
	v_writelane_b32 v254, s45, 36
	v_writelane_b32 v254, s46, 37
	v_writelane_b32 v254, s47, 38
	v_writelane_b32 v254, s48, 39
	v_writelane_b32 v254, s49, 40
	v_writelane_b32 v254, s50, 41
	v_writelane_b32 v254, s51, 42
	s_load_dwordx16 s[36:51], s[0:1], 0x80
	s_waitcnt lgkmcnt(0)
	v_writelane_b32 v254, s36, 43
	s_nop 1
	v_writelane_b32 v254, s37, 44
	v_writelane_b32 v254, s38, 45
	v_writelane_b32 v254, s39, 46
	v_writelane_b32 v254, s40, 47
	v_writelane_b32 v254, s41, 48
	v_writelane_b32 v254, s42, 49
	v_writelane_b32 v254, s43, 50
	v_writelane_b32 v254, s44, 51
	v_writelane_b32 v254, s45, 52
	v_writelane_b32 v254, s46, 53
	v_writelane_b32 v254, s47, 54
	v_writelane_b32 v254, s48, 55
	v_writelane_b32 v254, s49, 56
	v_writelane_b32 v254, s50, 57
	v_writelane_b32 v254, s51, 58
	v_writelane_b32 v254, s2, 59
	v_writelane_b32 v254, s6, 60
	s_nop 1
	v_writelane_b32 v254, s7, 61
	s_mov_b32 vcc_lo, 0
	s_nop 0
	v_writelane_b32 v255, vcc_lo, 40
	s_branch .LBB0_8

.LBB0_41:
	s_andn2_saveexec_b64 s[4:5], s[4:5]
	s_cbranch_execz .LBB0_61
	v_readlane_b32 s6, v255, 40
	s_cmp_eq_u32 s6, 1
	s_cbranch_scc0 .Lbar_global
	s_mul_hi_u32 s6, s17, 0x1999999a
	s_mul_i32 s6, s6, 10
	s_sub_i32 s6, s17, s6
	s_lshr_b32 s7, 0x305, s6
	s_bitcmp1_b32 s7, 0
	s_cbranch_scc1 .Lbar_local
	s_cmp_eq_u32 s6, 1
	s_cbranch_scc0 .Lbar_global
	s_cmp_gt_u32 s17, 1
	s_cbranch_scc0 .Lbar_global
.Lbar_local:
	s_waitcnt vmcnt(0) lgkmcnt(0)
	buffer_inv sc1
	v_mov_b32_e32 v2, 1
	v_readlane_b32 s4, v253, 8
	v_readlane_b32 s5, v253, 9
	s_nop 4
	global_atomic_add v131, v2, s[4:5]
	s_waitcnt vmcnt(0)
	s_branch .LBB0_61
.Lbar_global:
	s_mov_b64 s[4:5], exec
	buffer_wbl2 sc1
	s_waitcnt lgkmcnt(0)
	s_waitcnt vmcnt(0)
	v_mbcnt_lo_u32_b32 v3, s4, 0
	v_mbcnt_hi_u32_b32 v3, s5, v3
	v_cmp_eq_u32_e32 vcc, 0, v3
	s_and_saveexec_b64 s[6:7], vcc
	s_cbranch_execz .LBB0_44
	s_bcnt1_i32_b64 s4, s[4:5]
	v_mov_b32_e32 v4, s4
	v_readlane_b32 s4, v253, 10
	v_readlane_b32 s5, v253, 11
	s_nop 4
	global_atomic_add v4, v131, v4, s[4:5] sc0

.LBB0_61:
	s_cmp_eq_u32 s17, 1
	s_cbranch_scc0 .Lbar_chk_done
	s_mov_b64 exec, 1
	v_readlane_b32 s4, v252, 4
	v_readlane_b32 s5, v252, 5
	v_mov_b32_e32 v3, 0x3400
	s_nop 3
	global_load_dwordx4 v[4:7], v3, s[4:5] sc1
	global_load_dwordx4 v[8:11], v3, s[4:5] offset:16 sc1
	s_mov_b32 s10, 0
	s_mov_b32 s11, 1
	s_waitcnt vmcnt(0)
	v_readfirstlane_b32 s6, v4
	s_bcnt1_i32_b32 s7, s6
	s_cmp_eq_u32 s7, 1
	s_cselect_b32 s11, s11, 0
	s_or_b32 s10, s10, s6
	v_readfirstlane_b32 s6, v5
	s_bcnt1_i32_b32 s7, s6
	s_cmp_eq_u32 s7, 1
	s_cselect_b32 s11, s11, 0
	s_or_b32 s10, s10, s6
	v_readfirstlane_b32 s6, v6
	s_bcnt1_i32_b32 s7, s6
	s_cmp_eq_u32 s7, 1
	s_cselect_b32 s11, s11, 0
	s_or_b32 s10, s10, s6
	v_readfirstlane_b32 s6, v7
	s_bcnt1_i32_b32 s7, s6
	s_cmp_eq_u32 s7, 1
	s_cselect_b32 s11, s11, 0
	s_or_b32 s10, s10, s6
	v_readfirstlane_b32 s6, v8
	s_bcnt1_i32_b32 s7, s6
	s_cmp_eq_u32 s7, 1
	s_cselect_b32 s11, s11, 0
	s_or_b32 s10, s10, s6
	v_readfirstlane_b32 s6, v9
	s_bcnt1_i32_b32 s7, s6
	s_cmp_eq_u32 s7, 1
	s_cselect_b32 s11, s11, 0
	s_or_b32 s10, s10, s6
	v_readfirstlane_b32 s6, v10
	s_bcnt1_i32_b32 s7, s6
	s_cmp_eq_u32 s7, 1
	s_cselect_b32 s11, s11, 0
	s_or_b32 s10, s10, s6
	v_readfirstlane_b32 s6, v11
	s_bcnt1_i32_b32 s7, s6
	s_cmp_eq_u32 s7, 1
	s_cselect_b32 s11, s11, 0
	s_or_b32 s10, s10, s6
	s_bcnt1_i32_b32 s7, s10
	s_cmp_eq_u32 s7, 8
	s_cselect_b32 s11, s11, 0
	s_nop 0
	v_writelane_b32 v255, s11, 40
